# P10 SwiGLU epilogue: 8 sumsq loads hoisted before the epilogue with counted vmcnt(7) waits
# baseline (speedup 1.0000x reference)
.LBB0_1337:
	ds_read_b128 v[142:145], v149
	ds_read_b128 v[154:157], v149 offset:1024
	ds_read_b128 v[158:161], v149 offset:2048
	ds_read_b128 v[166:169], v149 offset:3072
	ds_read_b128 v[170:173], v150
	ds_read_b128 v[174:177], v150 offset:1024
	ds_read_b128 v[178:181], v150 offset:2048
	ds_read_b128 v[182:185], v150 offset:3072
	s_add_u32 s30, s28, 0xfff80080
	s_addc_u32 s31, s29, -1
	s_cmp_eq_u32 s54, 28
	s_cselect_b32 s35, s17, s31
	s_cselect_b32 s34, s19, s30
	s_cselect_b32 s31, s50, s53
	s_cselect_b32 s30, s51, s52
	v_lshl_add_u64 v[162:163], s[28:29], 0, v[138:139]
	s_add_i32 m0, s25, 0xc000
	ds_read_b128 v[186:189], v151
	ds_read_b128 v[190:193], v151 offset:1024
	ds_read_b128 v[194:197], v151 offset:2048
	ds_read_b128 v[198:201], v151 offset:3072
	ds_read_b128 v[202:205], v151 offset:4096
	ds_read_b128 v[206:209], v151 offset:5120
	ds_read_b128 v[210:213], v151 offset:6144
	ds_read_b128 v[214:217], v151 offset:7168
	global_load_lds_dwordx4 v[162:163], off
	v_lshl_add_u64 v[162:163], s[28:29], 0, v[140:141]
	s_add_i32 m0, s25, 0xe000
	s_nop 0
	global_load_lds_dwordx4 v[162:163], off
	s_waitcnt vmcnt(8)
	s_waitcnt lgkmcnt(0)
	s_barrier
	s_setprio 1
	s_waitcnt lgkmcnt(0)
	v_mfma_f32_16x16x32_bf16 v[122:125], v[142:145], v[186:189], v[122:125]
	v_mfma_f32_16x16x32_bf16 v[114:117], v[158:161], v[186:189], v[114:117]
	v_mfma_f32_16x16x32_bf16 v[106:109], v[142:145], v[194:197], v[106:109]
	v_mfma_f32_16x16x32_bf16 v[98:101], v[158:161], v[194:197], v[98:101]
	v_mfma_f32_16x16x32_bf16 v[90:93], v[142:145], v[202:205], v[90:93]
	v_mfma_f32_16x16x32_bf16 v[82:85], v[158:161], v[202:205], v[82:85]
	v_mfma_f32_16x16x32_bf16 v[74:77], v[142:145], v[210:213], v[74:77]
	v_mfma_f32_16x16x32_bf16 v[66:69], v[158:161], v[210:213], v[66:69]
	v_mfma_f32_16x16x32_bf16 v[122:125], v[154:157], v[190:193], v[122:125]
	v_mfma_f32_16x16x32_bf16 v[114:117], v[166:169], v[190:193], v[114:117]
	v_mfma_f32_16x16x32_bf16 v[106:109], v[154:157], v[198:201], v[106:109]
	v_mfma_f32_16x16x32_bf16 v[98:101], v[166:169], v[198:201], v[98:101]
	v_mfma_f32_16x16x32_bf16 v[90:93], v[154:157], v[206:209], v[90:93]
	v_mfma_f32_16x16x32_bf16 v[82:85], v[166:169], v[206:209], v[82:85]
	v_mfma_f32_16x16x32_bf16 v[74:77], v[154:157], v[214:217], v[74:77]
	v_mfma_f32_16x16x32_bf16 v[66:69], v[166:169], v[214:217], v[66:69]
	s_setprio 0
	s_setprio 1
	v_mfma_f32_16x16x32_bf16 v[126:129], v[170:173], v[186:189], v[126:129]
	v_mfma_f32_16x16x32_bf16 v[118:121], v[178:181], v[186:189], v[118:121]
	v_mfma_f32_16x16x32_bf16 v[110:113], v[170:173], v[194:197], v[110:113]
	v_mfma_f32_16x16x32_bf16 v[102:105], v[178:181], v[194:197], v[102:105]
	v_mfma_f32_16x16x32_bf16 v[94:97], v[170:173], v[202:205], v[94:97]
	v_mfma_f32_16x16x32_bf16 v[86:89], v[178:181], v[202:205], v[86:89]
	v_mfma_f32_16x16x32_bf16 v[78:81], v[170:173], v[210:213], v[78:81]
	v_mfma_f32_16x16x32_bf16 v[70:73], v[178:181], v[210:213], v[70:73]
	v_mfma_f32_16x16x32_bf16 v[126:129], v[174:177], v[190:193], v[126:129]
	v_mfma_f32_16x16x32_bf16 v[118:121], v[182:185], v[190:193], v[118:121]
	v_mfma_f32_16x16x32_bf16 v[110:113], v[174:177], v[198:201], v[110:113]
	v_mfma_f32_16x16x32_bf16 v[102:105], v[182:185], v[198:201], v[102:105]
	v_mfma_f32_16x16x32_bf16 v[94:97], v[174:177], v[206:209], v[94:97]
	v_mfma_f32_16x16x32_bf16 v[86:89], v[182:185], v[206:209], v[86:89]
	v_mfma_f32_16x16x32_bf16 v[78:81], v[174:177], v[214:217], v[78:81]
	v_mfma_f32_16x16x32_bf16 v[70:73], v[182:185], v[214:217], v[70:73]
	s_setprio 0
	s_barrier
	s_add_i32 s55, s46, s36
	v_lshl_add_u64 v[162:163], s[30:31], 0, v[132:133]
	s_mov_b32 m0, s55
	ds_read_b128 v[186:189], v151 offset:16384
	ds_read_b128 v[190:193], v151 offset:17408
	ds_read_b128 v[194:197], v151 offset:18432
	ds_read_b128 v[198:201], v151 offset:19456
	ds_read_b128 v[202:205], v151 offset:20480
	ds_read_b128 v[206:209], v151 offset:21504
	ds_read_b128 v[210:213], v151 offset:22528
	ds_read_b128 v[214:217], v151 offset:23552
	global_load_lds_dwordx4 v[162:163], off
	s_add_i32 m0, s55, 0x2000
	s_add_u32 s56, s30, 0x80000
	v_lshl_add_u64 v[218:219], s[30:31], 0, v[136:137]
	s_addc_u32 s57, s31, 0
	s_add_i32 s55, s47, s36
	global_load_lds_dwordx4 v[218:219], off
	v_lshl_add_u64 v[220:221], s[56:57], 0, v[132:133]
	s_mov_b32 m0, s55
	v_lshl_add_u64 v[222:223], s[34:35], 0, v[134:135]
	global_load_lds_dwordx4 v[220:221], off
	v_lshl_add_u64 v[220:221], s[56:57], 0, v[136:137]
	s_add_i32 m0, s55, 0x2000
	s_nop 0
	global_load_lds_dwordx4 v[220:221], off
	v_lshl_add_u64 v[220:221], s[34:35], 0, v[130:131]
	s_mov_b32 m0, s25
	s_nop 0
	global_load_lds_dwordx4 v[220:221], off
	s_mov_b32 m0, s27
	s_nop 0
	global_load_lds_dwordx4 v[222:223], off
	s_waitcnt vmcnt(8)
	s_waitcnt lgkmcnt(0)
	s_barrier
	s_setprio 1
	s_waitcnt lgkmcnt(0)
	v_mfma_f32_16x16x32_bf16 v[58:61], v[142:145], v[186:189], v[58:61]
	v_mfma_f32_16x16x32_bf16 v[50:53], v[158:161], v[186:189], v[50:53]
	v_mfma_f32_16x16x32_bf16 v[42:45], v[142:145], v[194:197], v[42:45]
	v_mfma_f32_16x16x32_bf16 v[34:37], v[158:161], v[194:197], v[34:37]
	v_mfma_f32_16x16x32_bf16 v[26:29], v[142:145], v[202:205], v[26:29]
	v_mfma_f32_16x16x32_bf16 v[18:21], v[158:161], v[202:205], v[18:21]
	v_mfma_f32_16x16x32_bf16 v[10:13], v[142:145], v[210:213], v[10:13]
	v_mfma_f32_16x16x32_bf16 v[2:5], v[158:161], v[210:213], v[2:5]
	v_mfma_f32_16x16x32_bf16 v[58:61], v[154:157], v[190:193], v[58:61]
	v_mfma_f32_16x16x32_bf16 v[50:53], v[166:169], v[190:193], v[50:53]
	v_mfma_f32_16x16x32_bf16 v[42:45], v[154:157], v[198:201], v[42:45]
	v_mfma_f32_16x16x32_bf16 v[34:37], v[166:169], v[198:201], v[34:37]
	v_mfma_f32_16x16x32_bf16 v[26:29], v[154:157], v[206:209], v[26:29]
	v_mfma_f32_16x16x32_bf16 v[18:21], v[166:169], v[206:209], v[18:21]
	v_mfma_f32_16x16x32_bf16 v[10:13], v[154:157], v[214:217], v[10:13]
	v_mfma_f32_16x16x32_bf16 v[2:5], v[166:169], v[214:217], v[2:5]
	s_setprio 0
	s_setprio 1
	v_mfma_f32_16x16x32_bf16 v[62:65], v[170:173], v[186:189], v[62:65]
	v_mfma_f32_16x16x32_bf16 v[54:57], v[178:181], v[186:189], v[54:57]
	v_mfma_f32_16x16x32_bf16 v[46:49], v[170:173], v[194:197], v[46:49]
	v_mfma_f32_16x16x32_bf16 v[38:41], v[178:181], v[194:197], v[38:41]
	v_mfma_f32_16x16x32_bf16 v[30:33], v[170:173], v[202:205], v[30:33]
	v_mfma_f32_16x16x32_bf16 v[22:25], v[178:181], v[202:205], v[22:25]
	v_mfma_f32_16x16x32_bf16 v[14:17], v[170:173], v[210:213], v[14:17]
	v_mfma_f32_16x16x32_bf16 v[6:9], v[178:181], v[210:213], v[6:9]
	v_mfma_f32_16x16x32_bf16 v[62:65], v[174:177], v[190:193], v[62:65]
	v_mfma_f32_16x16x32_bf16 v[54:57], v[182:185], v[190:193], v[54:57]
	v_mfma_f32_16x16x32_bf16 v[46:49], v[174:177], v[198:201], v[46:49]
	v_mfma_f32_16x16x32_bf16 v[38:41], v[182:185], v[198:201], v[38:41]
	v_mfma_f32_16x16x32_bf16 v[30:33], v[174:177], v[206:209], v[30:33]
	v_mfma_f32_16x16x32_bf16 v[22:25], v[182:185], v[206:209], v[22:25]
	v_mfma_f32_16x16x32_bf16 v[14:17], v[174:177], v[214:217], v[14:17]
	v_mfma_f32_16x16x32_bf16 v[6:9], v[182:185], v[214:217], v[6:9]
	s_setprio 0
	s_barrier
	s_add_i32 s55, 0, 0x18000
	v_add_u32_e32 v153, s55, v148
	s_add_i32 s56, 0, 0x1c000
	ds_read_b128 v[142:145], v153
	ds_read_b128 v[154:157], v153 offset:1024
	ds_read_b128 v[158:161], v153 offset:2048
	ds_read_b128 v[166:169], v153 offset:3072
	v_add_u32_e32 v153, s56, v148
	ds_read_b128 v[170:173], v153
	ds_read_b128 v[174:177], v153 offset:1024
	ds_read_b128 v[178:181], v153 offset:2048
	ds_read_b128 v[182:185], v153 offset:3072
	s_add_u32 s34, s34, 0x80000
	s_addc_u32 s35, s35, 0
	s_mov_b32 m0, s37
	v_lshl_add_u64 v[224:225], s[34:35], 0, v[130:131]
	ds_read_b128 v[186:189], v151 offset:32768
	ds_read_b128 v[190:193], v151 offset:33792
	ds_read_b128 v[194:197], v151 offset:34816
	ds_read_b128 v[198:201], v151 offset:35840
	ds_read_b128 v[202:205], v151 offset:36864
	ds_read_b128 v[206:209], v151 offset:37888
	ds_read_b128 v[210:213], v151 offset:38912
	ds_read_b128 v[214:217], v151 offset:39936
	global_load_lds_dwordx4 v[224:225], off
	v_lshl_add_u64 v[224:225], s[34:35], 0, v[134:135]
	s_mov_b32 m0, s38
	s_nop 0
	global_load_lds_dwordx4 v[224:225], off
	s_waitcnt vmcnt(8)
	s_waitcnt lgkmcnt(0)
	s_barrier
	s_setprio 1
	s_waitcnt lgkmcnt(0)
	v_mfma_f32_16x16x32_bf16 v[122:125], v[142:145], v[186:189], v[122:125]
	v_mfma_f32_16x16x32_bf16 v[114:117], v[158:161], v[186:189], v[114:117]
	v_mfma_f32_16x16x32_bf16 v[106:109], v[142:145], v[194:197], v[106:109]
	v_mfma_f32_16x16x32_bf16 v[98:101], v[158:161], v[194:197], v[98:101]
	v_mfma_f32_16x16x32_bf16 v[90:93], v[142:145], v[202:205], v[90:93]
	v_mfma_f32_16x16x32_bf16 v[82:85], v[158:161], v[202:205], v[82:85]
	v_mfma_f32_16x16x32_bf16 v[74:77], v[142:145], v[210:213], v[74:77]
	v_mfma_f32_16x16x32_bf16 v[66:69], v[158:161], v[210:213], v[66:69]
	v_mfma_f32_16x16x32_bf16 v[122:125], v[154:157], v[190:193], v[122:125]
	v_mfma_f32_16x16x32_bf16 v[114:117], v[166:169], v[190:193], v[114:117]
	v_mfma_f32_16x16x32_bf16 v[106:109], v[154:157], v[198:201], v[106:109]
	v_mfma_f32_16x16x32_bf16 v[98:101], v[166:169], v[198:201], v[98:101]
	v_mfma_f32_16x16x32_bf16 v[90:93], v[154:157], v[206:209], v[90:93]
	v_mfma_f32_16x16x32_bf16 v[82:85], v[166:169], v[206:209], v[82:85]
	v_mfma_f32_16x16x32_bf16 v[74:77], v[154:157], v[214:217], v[74:77]
	v_mfma_f32_16x16x32_bf16 v[66:69], v[166:169], v[214:217], v[66:69]
	s_setprio 0
	s_setprio 1
	v_mfma_f32_16x16x32_bf16 v[126:129], v[170:173], v[186:189], v[126:129]
	v_mfma_f32_16x16x32_bf16 v[118:121], v[178:181], v[186:189], v[118:121]
	v_mfma_f32_16x16x32_bf16 v[110:113], v[170:173], v[194:197], v[110:113]
	v_mfma_f32_16x16x32_bf16 v[102:105], v[178:181], v[194:197], v[102:105]
	v_mfma_f32_16x16x32_bf16 v[94:97], v[170:173], v[202:205], v[94:97]
	v_mfma_f32_16x16x32_bf16 v[86:89], v[178:181], v[202:205], v[86:89]
	v_mfma_f32_16x16x32_bf16 v[78:81], v[170:173], v[210:213], v[78:81]
	v_mfma_f32_16x16x32_bf16 v[70:73], v[178:181], v[210:213], v[70:73]
	v_mfma_f32_16x16x32_bf16 v[126:129], v[174:177], v[190:193], v[126:129]
	v_mfma_f32_16x16x32_bf16 v[118:121], v[182:185], v[190:193], v[118:121]
	v_mfma_f32_16x16x32_bf16 v[110:113], v[174:177], v[198:201], v[110:113]
	v_mfma_f32_16x16x32_bf16 v[102:105], v[182:185], v[198:201], v[102:105]
	v_mfma_f32_16x16x32_bf16 v[94:97], v[174:177], v[206:209], v[94:97]
	v_mfma_f32_16x16x32_bf16 v[86:89], v[182:185], v[206:209], v[86:89]
	v_mfma_f32_16x16x32_bf16 v[78:81], v[174:177], v[214:217], v[78:81]
	v_mfma_f32_16x16x32_bf16 v[70:73], v[182:185], v[214:217], v[70:73]
	s_setprio 0
	s_barrier
	s_add_i32 s34, s55, s36
	v_lshl_add_u64 v[162:163], v[162:163], 0, s[12:13]
	s_mov_b32 m0, s34
	ds_read_b128 v[186:189], v151 offset:49152
	ds_read_b128 v[190:193], v151 offset:50176
	ds_read_b128 v[194:197], v151 offset:51200
	ds_read_b128 v[198:201], v151 offset:52224
	ds_read_b128 v[202:205], v151 offset:53248
	ds_read_b128 v[206:209], v151 offset:54272
	ds_read_b128 v[210:213], v151 offset:55296
	ds_read_b128 v[214:217], v151 offset:56320
	global_load_lds_dwordx4 v[162:163], off
	s_add_i32 m0, s34, 0x2000
	s_add_u32 s30, s30, 0x80080
	v_lshl_add_u64 v[162:163], v[218:219], 0, s[12:13]
	s_addc_u32 s31, s31, 0
	s_add_i32 s34, s56, s36
	global_load_lds_dwordx4 v[162:163], off
	v_lshl_add_u64 v[162:163], s[30:31], 0, v[132:133]
	s_mov_b32 m0, s34
	s_nop 0
	global_load_lds_dwordx4 v[162:163], off
	v_lshl_add_u64 v[162:163], s[30:31], 0, v[136:137]
	s_add_i32 m0, s34, 0x2000
	s_nop 0
	global_load_lds_dwordx4 v[162:163], off
	v_lshl_add_u64 v[162:163], v[220:221], 0, s[12:13]
	s_mov_b32 m0, s42
	s_nop 0
	global_load_lds_dwordx4 v[162:163], off
	v_lshl_add_u64 v[162:163], v[222:223], 0, s[12:13]
	s_mov_b32 m0, s43
	s_nop 0
	global_load_lds_dwordx4 v[162:163], off
	s_waitcnt vmcnt(8)
	s_waitcnt lgkmcnt(0)
	s_barrier
	s_setprio 1
	s_waitcnt lgkmcnt(0)
	v_mfma_f32_16x16x32_bf16 v[58:61], v[142:145], v[186:189], v[58:61]
	v_mfma_f32_16x16x32_bf16 v[50:53], v[158:161], v[186:189], v[50:53]
	v_mfma_f32_16x16x32_bf16 v[42:45], v[142:145], v[194:197], v[42:45]
	v_mfma_f32_16x16x32_bf16 v[34:37], v[158:161], v[194:197], v[34:37]
	v_mfma_f32_16x16x32_bf16 v[26:29], v[142:145], v[202:205], v[26:29]
	v_mfma_f32_16x16x32_bf16 v[18:21], v[158:161], v[202:205], v[18:21]
	v_mfma_f32_16x16x32_bf16 v[10:13], v[142:145], v[210:213], v[10:13]
	v_mfma_f32_16x16x32_bf16 v[2:5], v[158:161], v[210:213], v[2:5]
	v_mfma_f32_16x16x32_bf16 v[58:61], v[154:157], v[190:193], v[58:61]
	v_mfma_f32_16x16x32_bf16 v[50:53], v[166:169], v[190:193], v[50:53]
	v_mfma_f32_16x16x32_bf16 v[42:45], v[154:157], v[198:201], v[42:45]
	v_mfma_f32_16x16x32_bf16 v[34:37], v[166:169], v[198:201], v[34:37]
	v_mfma_f32_16x16x32_bf16 v[26:29], v[154:157], v[206:209], v[26:29]
	v_mfma_f32_16x16x32_bf16 v[18:21], v[166:169], v[206:209], v[18:21]
	v_mfma_f32_16x16x32_bf16 v[10:13], v[154:157], v[214:217], v[10:13]
	v_mfma_f32_16x16x32_bf16 v[2:5], v[166:169], v[214:217], v[2:5]
	s_setprio 0
	s_setprio 1
	v_mfma_f32_16x16x32_bf16 v[62:65], v[170:173], v[186:189], v[62:65]
	v_mfma_f32_16x16x32_bf16 v[54:57], v[178:181], v[186:189], v[54:57]
	v_mfma_f32_16x16x32_bf16 v[46:49], v[170:173], v[194:197], v[46:49]
	v_mfma_f32_16x16x32_bf16 v[38:41], v[178:181], v[194:197], v[38:41]
	v_mfma_f32_16x16x32_bf16 v[30:33], v[170:173], v[202:205], v[30:33]
	v_mfma_f32_16x16x32_bf16 v[22:25], v[178:181], v[202:205], v[22:25]
	v_mfma_f32_16x16x32_bf16 v[14:17], v[170:173], v[210:213], v[14:17]
	v_mfma_f32_16x16x32_bf16 v[6:9], v[178:181], v[210:213], v[6:9]
	v_mfma_f32_16x16x32_bf16 v[62:65], v[174:177], v[190:193], v[62:65]
	v_mfma_f32_16x16x32_bf16 v[54:57], v[182:185], v[190:193], v[54:57]
	v_mfma_f32_16x16x32_bf16 v[46:49], v[174:177], v[198:201], v[46:49]
	v_mfma_f32_16x16x32_bf16 v[38:41], v[182:185], v[198:201], v[38:41]
	v_mfma_f32_16x16x32_bf16 v[30:33], v[174:177], v[206:209], v[30:33]
	v_mfma_f32_16x16x32_bf16 v[22:25], v[182:185], v[206:209], v[22:25]
	v_mfma_f32_16x16x32_bf16 v[14:17], v[174:177], v[214:217], v[14:17]
	v_mfma_f32_16x16x32_bf16 v[6:9], v[182:185], v[214:217], v[6:9]
	s_setprio 0
	s_barrier
	s_add_i32 s54, s54, 2
	s_add_u32 s28, s28, 0x100
	s_addc_u32 s29, s29, 0
	s_add_u32 s52, s52, 0x100
	s_addc_u32 s53, s53, 0
	s_cmp_gt_u32 s54, 29
	s_cbranch_scc0 .LBB0_1337
	v_mov_b32_e32 v142, v1
	v_mov_b32_e32 v153, v147
	v_mov_b32_e32 v143, v165
	v_mov_b32_e32 v144, v146
	s_lshl_b32 s17, s26, 8
	s_add_i32 s17, s17, s40
	v_add_u32_e32 v142, s17, v144
	v_ashrrev_i32_e32 v143, 31, v142
	v_lshl_add_u64 v[144:145], v[142:143], 2, s[10:11]
	global_load_dword v229, v[144:145], off
	global_load_dword v230, v[144:145], off offset:64
	global_load_dword v231, v[144:145], off offset:128
	global_load_dword v232, v[144:145], off offset:192
	global_load_dword v233, v[144:145], off offset:512
	global_load_dword v234, v[144:145], off offset:576
	global_load_dword v235, v[144:145], off offset:640
	global_load_dword v236, v[144:145], off offset:704
	s_and_b64 vcc, exec, s[14:15]
	s_cbranch_vccz .LBB0_1340
	s_barrier
.LBB0_1340:
	s_lshl_b32 s17, s24, 7
	s_or_b32 s17, s17, s41
	v_mov_b32_e32 v156, v120
	v_lshl_add_u32 v120, v153, 3, s17
	v_mov_b32_e32 v157, v116
	v_mov_b32_e32 v116, v121
	v_mov_b32_e32 v154, v126
	v_mov_b32_e32 v155, v122
	v_mov_b32_e32 v122, v127
	v_mov_b32_e32 v126, v128
	v_mov_b32_e32 v127, v124
	v_mov_b32_e32 v124, v129
	v_mov_b32_e32 v128, v118
	v_mov_b32_e32 v129, v114
	v_mov_b32_e32 v114, v119
	v_mov_b64_e32 v[118:119], s[64:65]
	v_ashrrev_i32_e32 v121, 31, v120
	v_mad_i64_i32 v[158:159], s[28:29], v142, s49, v[118:119]
	v_lshlrev_b64 v[120:121], 1, v[120:121]
	v_lshl_add_u64 v[158:159], v[158:159], 0, v[120:121]
	s_waitcnt vmcnt(7)
	v_fmamk_f32 v143, v229, 0x3a000000, v152
	v_mul_f32_e32 v153, 0x4b800000, v143
	v_cmp_gt_f32_e32 vcc, s48, v143
	s_nop 1
	v_cndmask_b32_e32 v143, v143, v153, vcc
	v_rsq_f32_e32 v143, v143
	s_nop 0
	v_mul_f32_e32 v153, 0x45800000, v143
	v_cndmask_b32_e32 v160, v143, v153, vcc
	v_pk_mul_f32 v[116:117], v[116:117], v[160:161] op_sel_hi:[1,0]
	v_pk_mul_f32 v[154:155], v[154:155], v[160:161] op_sel_hi:[1,0]
	v_pk_mul_f32 v[122:123], v[122:123], v[160:161] op_sel_hi:[1,0]
	v_pk_mul_f32 v[126:127], v[126:127], v[160:161] op_sel_hi:[1,0]
	v_pk_mul_f32 v[124:125], v[124:125], v[160:161] op_sel_hi:[1,0]
	v_pk_mul_f32 v[128:129], v[128:129], v[160:161] op_sel_hi:[1,0]
	v_pk_mul_f32 v[114:115], v[114:115], v[160:161] op_sel_hi:[1,0]
	v_pk_mul_f32 v[156:157], v[156:157], v[160:161] op_sel_hi:[1,0]
	v_mul_f32_e32 v166, 0xbfb8aa3b, v117
	v_mul_f32_e32 v143, 0xbfb8aa3b, v155
	v_mul_f32_e32 v153, 0xbfb8aa3b, v123
	v_mul_f32_e32 v160, 0xbfb8aa3b, v127
	v_mul_f32_e32 v161, 0xbfb8aa3b, v125
	v_mul_f32_e32 v162, 0xbfb8aa3b, v129
	v_mul_f32_e32 v163, 0xbfb8aa3b, v115
	v_mul_f32_e32 v164, 0xbfb8aa3b, v157
	v_exp_f32_e32 v166, v166
	v_exp_f32_e32 v143, v143
	v_exp_f32_e32 v153, v153
	v_exp_f32_e32 v160, v160
	v_exp_f32_e32 v161, v161
	v_exp_f32_e32 v162, v162
	v_exp_f32_e32 v163, v163
	v_exp_f32_e32 v164, v164
	v_add_f32_e32 v166, 1.0, v166
	v_add_f32_e32 v143, 1.0, v143
	v_add_f32_e32 v153, 1.0, v153
	v_add_f32_e32 v160, 1.0, v160
	v_add_f32_e32 v161, 1.0, v161
	v_add_f32_e32 v162, 1.0, v162
	v_add_f32_e32 v163, 1.0, v163
	v_add_f32_e32 v164, 1.0, v164
	v_rcp_f32_e32 v166, v166
	v_rcp_f32_e32 v143, v143
	v_rcp_f32_e32 v153, v153
	v_rcp_f32_e32 v160, v160
	v_rcp_f32_e32 v161, v161
	v_rcp_f32_e32 v162, v162
	v_rcp_f32_e32 v163, v163
	v_rcp_f32_e32 v164, v164
	v_mul_f32_e32 v117, v117, v166
	v_mul_f32_e32 v143, v155, v143
	v_mul_f32_e32 v123, v123, v153
	v_mul_f32_e32 v127, v127, v160
	v_mul_f32_e32 v125, v125, v161
	v_mul_f32_e32 v129, v129, v162
	v_mul_f32_e32 v115, v115, v163
	v_mul_f32_e32 v153, v157, v164
	v_mul_f32_e32 v117, v116, v117
	v_mul_f32_e32 v143, v154, v143
	v_mul_f32_e32 v122, v122, v123
	v_mul_f32_e32 v123, v126, v127
	v_mul_f32_e32 v124, v124, v125
	v_mul_f32_e32 v125, v128, v129
	v_mul_f32_e32 v126, v114, v115
	v_mul_f32_e32 v127, v156, v153
	v_cvt_pk_bf16_f32 v114, v143, v122
	v_cvt_pk_bf16_f32 v115, v123, v124
	v_cvt_pk_bf16_f32 v116, v125, v126
	v_cvt_pk_bf16_f32 v117, v127, v117
	global_store_dwordx4 v[158:159], v[114:117], off
	s_nop 0
	s_nop 0
	v_mov_b32_e32 v115, v106
	v_mov_b32_e32 v106, v111
	v_mov_b32_e32 v111, v108
	v_mov_b32_e32 v108, v113
	v_mov_b32_e32 v113, v98
	v_mov_b32_e32 v98, v103
	v_mov_b32_e32 v103, v100
	v_mov_b32_e32 v100, v105
	v_mov_b32_e32 v114, v110
	v_mov_b32_e32 v110, v112
	v_mov_b32_e32 v112, v102
	v_mov_b32_e32 v102, v104
	v_add_u32_e32 v104, 16, v142
	s_waitcnt vmcnt(7)
	v_fmamk_f32 v105, v230, 0x3a000000, v152
	v_mul_f32_e32 v116, 0x4b800000, v105
	v_cmp_gt_f32_e32 vcc, s48, v105
	s_nop 1
	v_cndmask_b32_e32 v105, v105, v116, vcc
	v_rsq_f32_e32 v116, v105
	v_mad_i64_i32 v[104:105], s[28:29], v104, s49, v[118:119]
	v_lshl_add_u64 v[104:105], v[104:105], 0, v[120:121]
	v_mul_f32_e32 v117, 0x45800000, v116
	v_cndmask_b32_e32 v116, v116, v117, vcc
	v_pk_mul_f32 v[100:101], v[100:101], v[116:117] op_sel_hi:[1,0]
	v_pk_mul_f32 v[114:115], v[114:115], v[116:117] op_sel_hi:[1,0]
	v_pk_mul_f32 v[106:107], v[106:107], v[116:117] op_sel_hi:[1,0]
	v_pk_mul_f32 v[110:111], v[110:111], v[116:117] op_sel_hi:[1,0]
	v_pk_mul_f32 v[108:109], v[108:109], v[116:117] op_sel_hi:[1,0]
	v_pk_mul_f32 v[112:113], v[112:113], v[116:117] op_sel_hi:[1,0]
	v_pk_mul_f32 v[98:99], v[98:99], v[116:117] op_sel_hi:[1,0]
	v_pk_mul_f32 v[102:103], v[102:103], v[116:117] op_sel_hi:[1,0]
	v_mul_f32_e32 v127, 0xbfb8aa3b, v101
	v_mul_f32_e32 v116, 0xbfb8aa3b, v115
	v_mul_f32_e32 v117, 0xbfb8aa3b, v107
	v_mul_f32_e32 v122, 0xbfb8aa3b, v111
	v_mul_f32_e32 v123, 0xbfb8aa3b, v109
	v_mul_f32_e32 v124, 0xbfb8aa3b, v113
	v_mul_f32_e32 v125, 0xbfb8aa3b, v99
	v_mul_f32_e32 v126, 0xbfb8aa3b, v103
	v_exp_f32_e32 v127, v127
	v_exp_f32_e32 v116, v116
	v_exp_f32_e32 v117, v117
	v_exp_f32_e32 v122, v122
	v_exp_f32_e32 v123, v123
	v_exp_f32_e32 v124, v124
	v_exp_f32_e32 v125, v125
	v_exp_f32_e32 v126, v126
	v_add_f32_e32 v127, 1.0, v127
	v_add_f32_e32 v116, 1.0, v116
	v_add_f32_e32 v117, 1.0, v117
	v_add_f32_e32 v122, 1.0, v122
	v_add_f32_e32 v123, 1.0, v123
	v_add_f32_e32 v124, 1.0, v124
	v_add_f32_e32 v125, 1.0, v125
	v_add_f32_e32 v126, 1.0, v126
	v_rcp_f32_e32 v127, v127
	v_rcp_f32_e32 v116, v116
	v_rcp_f32_e32 v117, v117
	v_rcp_f32_e32 v122, v122
	v_rcp_f32_e32 v123, v123
	v_rcp_f32_e32 v124, v124
	v_rcp_f32_e32 v125, v125
	v_rcp_f32_e32 v126, v126
	v_mul_f32_e32 v101, v101, v127
	v_mul_f32_e32 v115, v115, v116
	v_mul_f32_e32 v107, v107, v117
	v_mul_f32_e32 v111, v111, v122
	v_mul_f32_e32 v109, v109, v123
	v_mul_f32_e32 v113, v113, v124
	v_mul_f32_e32 v99, v99, v125
	v_mul_f32_e32 v103, v103, v126
	v_mul_f32_e32 v101, v100, v101
	v_mul_f32_e32 v114, v114, v115
	v_mul_f32_e32 v106, v106, v107
	v_mul_f32_e32 v107, v110, v111
	v_mul_f32_e32 v108, v108, v109
	v_mul_f32_e32 v109, v112, v113
	v_mul_f32_e32 v110, v98, v99
	v_mul_f32_e32 v102, v102, v103
	v_cvt_pk_bf16_f32 v98, v114, v106
	v_cvt_pk_bf16_f32 v99, v107, v108
	v_cvt_pk_bf16_f32 v100, v109, v110
	v_cvt_pk_bf16_f32 v101, v102, v101
	global_store_dwordx4 v[104:105], v[98:101], off
	s_nop 0
	s_nop 0
	v_mov_b32_e32 v99, v90
	v_mov_b32_e32 v90, v95
	v_mov_b32_e32 v95, v92
	v_mov_b32_e32 v92, v97
	v_mov_b32_e32 v97, v82
	v_mov_b32_e32 v82, v87
	v_mov_b32_e32 v87, v84
	v_mov_b32_e32 v84, v89
	v_mov_b32_e32 v98, v94
	v_mov_b32_e32 v94, v96
	v_mov_b32_e32 v96, v86
	v_mov_b32_e32 v86, v88
	v_add_u32_e32 v88, 32, v142
	s_waitcnt vmcnt(7)
	v_fmamk_f32 v89, v231, 0x3a000000, v152
	v_mul_f32_e32 v100, 0x4b800000, v89
	v_cmp_gt_f32_e32 vcc, s48, v89
	s_nop 1
	v_cndmask_b32_e32 v89, v89, v100, vcc
	v_rsq_f32_e32 v100, v89
	v_mad_i64_i32 v[88:89], s[28:29], v88, s49, v[118:119]
	v_lshl_add_u64 v[88:89], v[88:89], 0, v[120:121]
	v_mul_f32_e32 v101, 0x45800000, v100
	v_cndmask_b32_e32 v100, v100, v101, vcc
	v_pk_mul_f32 v[84:85], v[84:85], v[100:101] op_sel_hi:[1,0]
	v_pk_mul_f32 v[98:99], v[98:99], v[100:101] op_sel_hi:[1,0]
	v_pk_mul_f32 v[90:91], v[90:91], v[100:101] op_sel_hi:[1,0]
	v_pk_mul_f32 v[94:95], v[94:95], v[100:101] op_sel_hi:[1,0]
	v_pk_mul_f32 v[92:93], v[92:93], v[100:101] op_sel_hi:[1,0]
	v_pk_mul_f32 v[96:97], v[96:97], v[100:101] op_sel_hi:[1,0]
	v_pk_mul_f32 v[82:83], v[82:83], v[100:101] op_sel_hi:[1,0]
	v_pk_mul_f32 v[86:87], v[86:87], v[100:101] op_sel_hi:[1,0]
	v_mul_f32_e32 v107, 0xbfb8aa3b, v85
	v_mul_f32_e32 v100, 0xbfb8aa3b, v99
	v_mul_f32_e32 v101, 0xbfb8aa3b, v91
	v_mul_f32_e32 v102, 0xbfb8aa3b, v95
	v_mul_f32_e32 v103, 0xbfb8aa3b, v93
	v_mul_f32_e32 v104, 0xbfb8aa3b, v97
	v_mul_f32_e32 v105, 0xbfb8aa3b, v83
	v_mul_f32_e32 v106, 0xbfb8aa3b, v87
	v_exp_f32_e32 v107, v107
	v_exp_f32_e32 v100, v100
	v_exp_f32_e32 v101, v101
	v_exp_f32_e32 v102, v102
	v_exp_f32_e32 v103, v103
	v_exp_f32_e32 v104, v104
	v_exp_f32_e32 v105, v105
	v_exp_f32_e32 v106, v106
	v_add_f32_e32 v107, 1.0, v107
	v_add_f32_e32 v100, 1.0, v100
	v_add_f32_e32 v101, 1.0, v101
	v_add_f32_e32 v102, 1.0, v102
	v_add_f32_e32 v103, 1.0, v103
	v_add_f32_e32 v104, 1.0, v104
	v_add_f32_e32 v105, 1.0, v105
	v_add_f32_e32 v106, 1.0, v106
	v_rcp_f32_e32 v107, v107
	v_rcp_f32_e32 v100, v100
	v_rcp_f32_e32 v101, v101
	v_rcp_f32_e32 v102, v102
	v_rcp_f32_e32 v103, v103
	v_rcp_f32_e32 v104, v104
	v_rcp_f32_e32 v105, v105
	v_rcp_f32_e32 v106, v106
	v_mul_f32_e32 v85, v85, v107
	v_mul_f32_e32 v99, v99, v100
	v_mul_f32_e32 v91, v91, v101
	v_mul_f32_e32 v95, v95, v102
	v_mul_f32_e32 v93, v93, v103
	v_mul_f32_e32 v97, v97, v104
	v_mul_f32_e32 v83, v83, v105
	v_mul_f32_e32 v87, v87, v106
	v_mul_f32_e32 v85, v84, v85
	v_mul_f32_e32 v98, v98, v99
	v_mul_f32_e32 v90, v90, v91
	v_mul_f32_e32 v91, v94, v95
	v_mul_f32_e32 v92, v92, v93
	v_mul_f32_e32 v93, v96, v97
	v_mul_f32_e32 v94, v82, v83
	v_mul_f32_e32 v86, v86, v87
	v_cvt_pk_bf16_f32 v82, v98, v90
	v_cvt_pk_bf16_f32 v83, v91, v92
	v_cvt_pk_bf16_f32 v84, v93, v94
	v_cvt_pk_bf16_f32 v85, v86, v85
	global_store_dwordx4 v[88:89], v[82:85], off
	s_nop 0
	s_nop 0
	v_mov_b32_e32 v83, v74
	v_mov_b32_e32 v74, v79
	v_mov_b32_e32 v79, v76
	v_mov_b32_e32 v76, v81
	v_mov_b32_e32 v81, v66
	v_mov_b32_e32 v66, v71
	v_mov_b32_e32 v71, v68
	v_mov_b32_e32 v68, v73
	v_mov_b32_e32 v82, v78
	v_mov_b32_e32 v78, v80
	v_mov_b32_e32 v80, v70
	v_mov_b32_e32 v70, v72
	v_add_u32_e32 v72, 48, v142
	s_waitcnt vmcnt(7)
	v_fmamk_f32 v73, v232, 0x3a000000, v152
	v_mul_f32_e32 v84, 0x4b800000, v73
	v_cmp_gt_f32_e32 vcc, s48, v73
	s_nop 1
	v_cndmask_b32_e32 v73, v73, v84, vcc
	v_rsq_f32_e32 v84, v73
	v_mad_i64_i32 v[72:73], s[28:29], v72, s49, v[118:119]
	v_lshl_add_u64 v[72:73], v[72:73], 0, v[120:121]
	v_mul_f32_e32 v85, 0x45800000, v84
	v_cndmask_b32_e32 v84, v84, v85, vcc
	v_pk_mul_f32 v[68:69], v[68:69], v[84:85] op_sel_hi:[1,0]
	v_pk_mul_f32 v[82:83], v[82:83], v[84:85] op_sel_hi:[1,0]
	v_pk_mul_f32 v[74:75], v[74:75], v[84:85] op_sel_hi:[1,0]
	v_pk_mul_f32 v[78:79], v[78:79], v[84:85] op_sel_hi:[1,0]
	v_pk_mul_f32 v[76:77], v[76:77], v[84:85] op_sel_hi:[1,0]
	v_pk_mul_f32 v[80:81], v[80:81], v[84:85] op_sel_hi:[1,0]
	v_pk_mul_f32 v[66:67], v[66:67], v[84:85] op_sel_hi:[1,0]
	v_pk_mul_f32 v[70:71], v[70:71], v[84:85] op_sel_hi:[1,0]
	v_mul_f32_e32 v91, 0xbfb8aa3b, v69
	v_mul_f32_e32 v84, 0xbfb8aa3b, v83
	v_mul_f32_e32 v85, 0xbfb8aa3b, v75
	v_mul_f32_e32 v86, 0xbfb8aa3b, v79
	v_mul_f32_e32 v87, 0xbfb8aa3b, v77
	v_mul_f32_e32 v88, 0xbfb8aa3b, v81
	v_mul_f32_e32 v89, 0xbfb8aa3b, v67
	v_mul_f32_e32 v90, 0xbfb8aa3b, v71
	v_exp_f32_e32 v91, v91
	v_exp_f32_e32 v84, v84
	v_exp_f32_e32 v85, v85
	v_exp_f32_e32 v86, v86
	v_exp_f32_e32 v87, v87
	v_exp_f32_e32 v88, v88
	v_exp_f32_e32 v89, v89
	v_exp_f32_e32 v90, v90
	v_add_f32_e32 v91, 1.0, v91
	v_add_f32_e32 v84, 1.0, v84
	v_add_f32_e32 v85, 1.0, v85
	v_add_f32_e32 v86, 1.0, v86
	v_add_f32_e32 v87, 1.0, v87
	v_add_f32_e32 v88, 1.0, v88
	v_add_f32_e32 v89, 1.0, v89
	v_add_f32_e32 v90, 1.0, v90
	v_rcp_f32_e32 v91, v91
	v_rcp_f32_e32 v84, v84
	v_rcp_f32_e32 v85, v85
	v_rcp_f32_e32 v86, v86
	v_rcp_f32_e32 v87, v87
	v_rcp_f32_e32 v88, v88
	v_rcp_f32_e32 v89, v89
	v_rcp_f32_e32 v90, v90
	v_mul_f32_e32 v69, v69, v91
	v_mul_f32_e32 v83, v83, v84
	v_mul_f32_e32 v75, v75, v85
	v_mul_f32_e32 v79, v79, v86
	v_mul_f32_e32 v77, v77, v87
	v_mul_f32_e32 v81, v81, v88
	v_mul_f32_e32 v67, v67, v89
	v_mul_f32_e32 v71, v71, v90
	v_mul_f32_e32 v69, v68, v69
	v_mul_f32_e32 v82, v82, v83
	v_mul_f32_e32 v74, v74, v75
	v_mul_f32_e32 v75, v78, v79
	v_mul_f32_e32 v76, v76, v77
	v_mul_f32_e32 v77, v80, v81
	v_mul_f32_e32 v78, v66, v67
	v_mul_f32_e32 v70, v70, v71
	v_cvt_pk_bf16_f32 v66, v82, v74
	v_cvt_pk_bf16_f32 v67, v75, v76
	v_cvt_pk_bf16_f32 v68, v77, v78
	v_cvt_pk_bf16_f32 v69, v70, v69
	global_store_dwordx4 v[72:73], v[66:69], off
	s_nop 0
	s_nop 0
	v_mov_b32_e32 v67, v58
	v_mov_b32_e32 v58, v63
	v_mov_b32_e32 v63, v60
	v_mov_b32_e32 v60, v65
	v_mov_b32_e32 v65, v50
	v_mov_b32_e32 v50, v55
	v_mov_b32_e32 v55, v52
	v_mov_b32_e32 v52, v57
	v_mov_b32_e32 v66, v62
	v_mov_b32_e32 v62, v64
	v_mov_b32_e32 v64, v54
	v_mov_b32_e32 v54, v56
	v_add_u32_e32 v56, 0x80, v142
	s_waitcnt vmcnt(7)
	v_fmamk_f32 v57, v233, 0x3a000000, v152
	v_mul_f32_e32 v68, 0x4b800000, v57
	v_cmp_gt_f32_e32 vcc, s48, v57
	s_nop 1
	v_cndmask_b32_e32 v57, v57, v68, vcc
	v_rsq_f32_e32 v68, v57
	v_mad_i64_i32 v[56:57], s[28:29], v56, s49, v[118:119]
	v_lshl_add_u64 v[56:57], v[56:57], 0, v[120:121]
	v_mul_f32_e32 v69, 0x45800000, v68
	v_cndmask_b32_e32 v68, v68, v69, vcc
	v_pk_mul_f32 v[52:53], v[52:53], v[68:69] op_sel_hi:[1,0]
	v_pk_mul_f32 v[66:67], v[66:67], v[68:69] op_sel_hi:[1,0]
	v_pk_mul_f32 v[58:59], v[58:59], v[68:69] op_sel_hi:[1,0]
	v_pk_mul_f32 v[62:63], v[62:63], v[68:69] op_sel_hi:[1,0]
	v_pk_mul_f32 v[60:61], v[60:61], v[68:69] op_sel_hi:[1,0]
	v_pk_mul_f32 v[64:65], v[64:65], v[68:69] op_sel_hi:[1,0]
	v_pk_mul_f32 v[50:51], v[50:51], v[68:69] op_sel_hi:[1,0]
	v_pk_mul_f32 v[54:55], v[54:55], v[68:69] op_sel_hi:[1,0]
	v_mul_f32_e32 v75, 0xbfb8aa3b, v53
	v_mul_f32_e32 v68, 0xbfb8aa3b, v67
	v_mul_f32_e32 v69, 0xbfb8aa3b, v59
	v_mul_f32_e32 v70, 0xbfb8aa3b, v63
	v_mul_f32_e32 v71, 0xbfb8aa3b, v61
	v_mul_f32_e32 v72, 0xbfb8aa3b, v65
	v_mul_f32_e32 v73, 0xbfb8aa3b, v51
	v_mul_f32_e32 v74, 0xbfb8aa3b, v55
	v_exp_f32_e32 v75, v75
	v_exp_f32_e32 v68, v68
	v_exp_f32_e32 v69, v69
	v_exp_f32_e32 v70, v70
	v_exp_f32_e32 v71, v71
	v_exp_f32_e32 v72, v72
	v_exp_f32_e32 v73, v73
	v_exp_f32_e32 v74, v74
	v_add_f32_e32 v75, 1.0, v75
	v_add_f32_e32 v68, 1.0, v68
	v_add_f32_e32 v69, 1.0, v69
	v_add_f32_e32 v70, 1.0, v70
	v_add_f32_e32 v71, 1.0, v71
	v_add_f32_e32 v72, 1.0, v72
	v_add_f32_e32 v73, 1.0, v73
	v_add_f32_e32 v74, 1.0, v74
	v_rcp_f32_e32 v75, v75
	v_rcp_f32_e32 v68, v68
	v_rcp_f32_e32 v69, v69
	v_rcp_f32_e32 v70, v70
	v_rcp_f32_e32 v71, v71
	v_rcp_f32_e32 v72, v72
	v_rcp_f32_e32 v73, v73
	v_rcp_f32_e32 v74, v74
	v_mul_f32_e32 v53, v53, v75
	v_mul_f32_e32 v67, v67, v68
	v_mul_f32_e32 v59, v59, v69
	v_mul_f32_e32 v63, v63, v70
	v_mul_f32_e32 v61, v61, v71
	v_mul_f32_e32 v65, v65, v72
	v_mul_f32_e32 v51, v51, v73
	v_mul_f32_e32 v55, v55, v74
	v_mul_f32_e32 v53, v52, v53
	v_mul_f32_e32 v66, v66, v67
	v_mul_f32_e32 v58, v58, v59
	v_mul_f32_e32 v59, v62, v63
	v_mul_f32_e32 v60, v60, v61
	v_mul_f32_e32 v61, v64, v65
	v_mul_f32_e32 v62, v50, v51
	v_mul_f32_e32 v54, v54, v55
	v_cvt_pk_bf16_f32 v50, v66, v58
	v_cvt_pk_bf16_f32 v51, v59, v60
	v_cvt_pk_bf16_f32 v52, v61, v62
	v_cvt_pk_bf16_f32 v53, v54, v53
	global_store_dwordx4 v[56:57], v[50:53], off
	s_nop 0
	s_nop 0
	v_mov_b32_e32 v51, v42
	v_mov_b32_e32 v42, v47
	v_mov_b32_e32 v47, v44
	v_mov_b32_e32 v44, v49
	v_mov_b32_e32 v49, v34
	v_mov_b32_e32 v34, v39
	v_mov_b32_e32 v39, v36
	v_mov_b32_e32 v36, v41
	v_mov_b32_e32 v50, v46
	v_mov_b32_e32 v46, v48
	v_mov_b32_e32 v48, v38
	v_mov_b32_e32 v38, v40
	v_add_u32_e32 v40, 0x90, v142
	s_waitcnt vmcnt(7)
	v_fmamk_f32 v41, v234, 0x3a000000, v152
	v_mul_f32_e32 v52, 0x4b800000, v41
	v_cmp_gt_f32_e32 vcc, s48, v41
	s_nop 1
	v_cndmask_b32_e32 v41, v41, v52, vcc
	v_rsq_f32_e32 v52, v41
	v_mad_i64_i32 v[40:41], s[28:29], v40, s49, v[118:119]
	v_lshl_add_u64 v[40:41], v[40:41], 0, v[120:121]
	v_mul_f32_e32 v53, 0x45800000, v52
	v_cndmask_b32_e32 v52, v52, v53, vcc
	v_pk_mul_f32 v[36:37], v[36:37], v[52:53] op_sel_hi:[1,0]
	v_pk_mul_f32 v[50:51], v[50:51], v[52:53] op_sel_hi:[1,0]
	v_pk_mul_f32 v[42:43], v[42:43], v[52:53] op_sel_hi:[1,0]
	v_pk_mul_f32 v[46:47], v[46:47], v[52:53] op_sel_hi:[1,0]
	v_pk_mul_f32 v[44:45], v[44:45], v[52:53] op_sel_hi:[1,0]
	v_pk_mul_f32 v[48:49], v[48:49], v[52:53] op_sel_hi:[1,0]
	v_pk_mul_f32 v[34:35], v[34:35], v[52:53] op_sel_hi:[1,0]
	v_pk_mul_f32 v[38:39], v[38:39], v[52:53] op_sel_hi:[1,0]
	v_mul_f32_e32 v59, 0xbfb8aa3b, v37
	v_mul_f32_e32 v52, 0xbfb8aa3b, v51
	v_mul_f32_e32 v53, 0xbfb8aa3b, v43
	v_mul_f32_e32 v54, 0xbfb8aa3b, v47
	v_mul_f32_e32 v55, 0xbfb8aa3b, v45
	v_mul_f32_e32 v56, 0xbfb8aa3b, v49
	v_mul_f32_e32 v57, 0xbfb8aa3b, v35
	v_mul_f32_e32 v58, 0xbfb8aa3b, v39
	v_exp_f32_e32 v59, v59
	v_exp_f32_e32 v52, v52
	v_exp_f32_e32 v53, v53
	v_exp_f32_e32 v54, v54
	v_exp_f32_e32 v55, v55
	v_exp_f32_e32 v56, v56
	v_exp_f32_e32 v57, v57
	v_exp_f32_e32 v58, v58
	v_add_f32_e32 v59, 1.0, v59
	v_add_f32_e32 v52, 1.0, v52
	v_add_f32_e32 v53, 1.0, v53
	v_add_f32_e32 v54, 1.0, v54
	v_add_f32_e32 v55, 1.0, v55
	v_add_f32_e32 v56, 1.0, v56
	v_add_f32_e32 v57, 1.0, v57
	v_add_f32_e32 v58, 1.0, v58
	v_rcp_f32_e32 v59, v59
	v_rcp_f32_e32 v52, v52
	v_rcp_f32_e32 v53, v53
	v_rcp_f32_e32 v54, v54
	v_rcp_f32_e32 v55, v55
	v_rcp_f32_e32 v56, v56
	v_rcp_f32_e32 v57, v57
	v_rcp_f32_e32 v58, v58
	v_mul_f32_e32 v37, v37, v59
	v_mul_f32_e32 v51, v51, v52
	v_mul_f32_e32 v43, v43, v53
	v_mul_f32_e32 v47, v47, v54
	v_mul_f32_e32 v45, v45, v55
	v_mul_f32_e32 v49, v49, v56
	v_mul_f32_e32 v35, v35, v57
	v_mul_f32_e32 v39, v39, v58
	v_mul_f32_e32 v37, v36, v37
	v_mul_f32_e32 v50, v50, v51
	v_mul_f32_e32 v42, v42, v43
	v_mul_f32_e32 v43, v46, v47
	v_mul_f32_e32 v44, v44, v45
	v_mul_f32_e32 v45, v48, v49
	v_mul_f32_e32 v46, v34, v35
	v_mul_f32_e32 v38, v38, v39
	v_cvt_pk_bf16_f32 v34, v50, v42
	v_cvt_pk_bf16_f32 v35, v43, v44
	v_cvt_pk_bf16_f32 v36, v45, v46
	v_cvt_pk_bf16_f32 v37, v38, v37
	global_store_dwordx4 v[40:41], v[34:37], off
	s_nop 0
	s_nop 0
	v_mov_b32_e32 v35, v26
	v_mov_b32_e32 v26, v31
	v_mov_b32_e32 v31, v28
	v_mov_b32_e32 v28, v33
	v_mov_b32_e32 v33, v18
	v_mov_b32_e32 v18, v23
	v_mov_b32_e32 v23, v20
	v_mov_b32_e32 v20, v25
	v_mov_b32_e32 v34, v30
	v_mov_b32_e32 v30, v32
	v_mov_b32_e32 v32, v22
	v_mov_b32_e32 v22, v24
	v_add_u32_e32 v24, 0xa0, v142
	s_waitcnt vmcnt(7)
	v_fmamk_f32 v25, v235, 0x3a000000, v152
	v_mul_f32_e32 v36, 0x4b800000, v25
	v_cmp_gt_f32_e32 vcc, s48, v25
	s_nop 1
	v_cndmask_b32_e32 v25, v25, v36, vcc
	v_rsq_f32_e32 v36, v25
	v_mad_i64_i32 v[24:25], s[28:29], v24, s49, v[118:119]
	v_lshl_add_u64 v[24:25], v[24:25], 0, v[120:121]
	v_mul_f32_e32 v37, 0x45800000, v36
	v_cndmask_b32_e32 v36, v36, v37, vcc
	v_pk_mul_f32 v[20:21], v[20:21], v[36:37] op_sel_hi:[1,0]
	v_pk_mul_f32 v[34:35], v[34:35], v[36:37] op_sel_hi:[1,0]
	v_pk_mul_f32 v[26:27], v[26:27], v[36:37] op_sel_hi:[1,0]
	v_pk_mul_f32 v[30:31], v[30:31], v[36:37] op_sel_hi:[1,0]
	v_pk_mul_f32 v[28:29], v[28:29], v[36:37] op_sel_hi:[1,0]
	v_pk_mul_f32 v[32:33], v[32:33], v[36:37] op_sel_hi:[1,0]
	v_pk_mul_f32 v[18:19], v[18:19], v[36:37] op_sel_hi:[1,0]
	v_pk_mul_f32 v[22:23], v[22:23], v[36:37] op_sel_hi:[1,0]
	v_mul_f32_e32 v43, 0xbfb8aa3b, v21
	v_mul_f32_e32 v36, 0xbfb8aa3b, v35
	v_mul_f32_e32 v37, 0xbfb8aa3b, v27
	v_mul_f32_e32 v38, 0xbfb8aa3b, v31
	v_mul_f32_e32 v39, 0xbfb8aa3b, v29
	v_mul_f32_e32 v40, 0xbfb8aa3b, v33
	v_mul_f32_e32 v41, 0xbfb8aa3b, v19
	v_mul_f32_e32 v42, 0xbfb8aa3b, v23
	v_exp_f32_e32 v43, v43
	v_exp_f32_e32 v36, v36
	v_exp_f32_e32 v37, v37
	v_exp_f32_e32 v38, v38
	v_exp_f32_e32 v39, v39
	v_exp_f32_e32 v40, v40
	v_exp_f32_e32 v41, v41
	v_exp_f32_e32 v42, v42
	v_add_f32_e32 v43, 1.0, v43
	v_add_f32_e32 v36, 1.0, v36
	v_add_f32_e32 v37, 1.0, v37
	v_add_f32_e32 v38, 1.0, v38
	v_add_f32_e32 v39, 1.0, v39
	v_add_f32_e32 v40, 1.0, v40
	v_add_f32_e32 v41, 1.0, v41
	v_add_f32_e32 v42, 1.0, v42
	v_rcp_f32_e32 v43, v43
	v_rcp_f32_e32 v36, v36
	v_rcp_f32_e32 v37, v37
	v_rcp_f32_e32 v38, v38
	v_rcp_f32_e32 v39, v39
	v_rcp_f32_e32 v40, v40
	v_rcp_f32_e32 v41, v41
	v_rcp_f32_e32 v42, v42
	v_mul_f32_e32 v21, v21, v43
	v_mul_f32_e32 v35, v35, v36
	v_mul_f32_e32 v27, v27, v37
	v_mul_f32_e32 v31, v31, v38
	v_mul_f32_e32 v29, v29, v39
	v_mul_f32_e32 v33, v33, v40
	v_mul_f32_e32 v19, v19, v41
	v_mul_f32_e32 v23, v23, v42
	v_mul_f32_e32 v21, v20, v21
	v_mul_f32_e32 v34, v34, v35
	v_mul_f32_e32 v26, v26, v27
	v_mul_f32_e32 v27, v30, v31
	v_mul_f32_e32 v28, v28, v29
	v_mul_f32_e32 v29, v32, v33
	v_mul_f32_e32 v30, v18, v19
	v_mul_f32_e32 v22, v22, v23
	v_cvt_pk_bf16_f32 v18, v34, v26
	v_cvt_pk_bf16_f32 v19, v27, v28
	v_cvt_pk_bf16_f32 v20, v29, v30
	v_cvt_pk_bf16_f32 v21, v22, v21
	global_store_dwordx4 v[24:25], v[18:21], off
	s_nop 0
	s_andn2_b64 vcc, exec, s[0:1]
	v_mov_b32_e32 v19, v10
	v_mov_b32_e32 v10, v15
	v_mov_b32_e32 v15, v12
	v_mov_b32_e32 v12, v17
	v_mov_b32_e32 v17, v2
	v_mov_b32_e32 v2, v7
	v_mov_b32_e32 v7, v4
	v_mov_b32_e32 v4, v9
	v_mov_b32_e32 v18, v14
	v_mov_b32_e32 v14, v16
	v_mov_b32_e32 v16, v6
	v_mov_b32_e32 v6, v8
	v_add_u32_e32 v8, 0xb0, v142
	s_waitcnt vmcnt(7)
	v_fmamk_f32 v9, v236, 0x3a000000, v152
	v_mul_f32_e32 v20, 0x4b800000, v9
	v_cmp_gt_f32_e64 s[0:1], s48, v9
	s_nop 1
	v_cndmask_b32_e64 v9, v9, v20, s[0:1]
	v_rsq_f32_e32 v20, v9
	v_mad_i64_i32 v[8:9], s[28:29], v8, s49, v[118:119]
	v_lshl_add_u64 v[8:9], v[8:9], 0, v[120:121]
	v_mul_f32_e32 v21, 0x45800000, v20
	v_cndmask_b32_e64 v20, v20, v21, s[0:1]
	v_pk_mul_f32 v[4:5], v[4:5], v[20:21] op_sel_hi:[1,0]
	v_pk_mul_f32 v[18:19], v[18:19], v[20:21] op_sel_hi:[1,0]
	v_pk_mul_f32 v[10:11], v[10:11], v[20:21] op_sel_hi:[1,0]
	v_pk_mul_f32 v[14:15], v[14:15], v[20:21] op_sel_hi:[1,0]
	v_pk_mul_f32 v[12:13], v[12:13], v[20:21] op_sel_hi:[1,0]
	v_pk_mul_f32 v[16:17], v[16:17], v[20:21] op_sel_hi:[1,0]
	v_pk_mul_f32 v[2:3], v[2:3], v[20:21] op_sel_hi:[1,0]
	v_pk_mul_f32 v[6:7], v[6:7], v[20:21] op_sel_hi:[1,0]
	v_mul_f32_e32 v27, 0xbfb8aa3b, v5
	v_mul_f32_e32 v20, 0xbfb8aa3b, v19
	v_mul_f32_e32 v21, 0xbfb8aa3b, v11
	v_mul_f32_e32 v22, 0xbfb8aa3b, v15
	v_mul_f32_e32 v23, 0xbfb8aa3b, v13
	v_mul_f32_e32 v24, 0xbfb8aa3b, v17
	v_mul_f32_e32 v25, 0xbfb8aa3b, v3
	v_mul_f32_e32 v26, 0xbfb8aa3b, v7
	v_exp_f32_e32 v27, v27
	v_exp_f32_e32 v20, v20
	v_exp_f32_e32 v21, v21
	v_exp_f32_e32 v22, v22
	v_exp_f32_e32 v23, v23
	v_exp_f32_e32 v24, v24
	v_exp_f32_e32 v25, v25
	v_exp_f32_e32 v26, v26
	v_add_f32_e32 v27, 1.0, v27
	v_add_f32_e32 v20, 1.0, v20
	v_add_f32_e32 v21, 1.0, v21
	v_add_f32_e32 v22, 1.0, v22
	v_add_f32_e32 v23, 1.0, v23
	v_add_f32_e32 v24, 1.0, v24
	v_add_f32_e32 v25, 1.0, v25
	v_add_f32_e32 v26, 1.0, v26
	v_rcp_f32_e32 v27, v27
	v_rcp_f32_e32 v20, v20
	v_rcp_f32_e32 v21, v21
	v_rcp_f32_e32 v22, v22
	v_rcp_f32_e32 v23, v23
	v_rcp_f32_e32 v24, v24
	v_rcp_f32_e32 v25, v25
	v_rcp_f32_e32 v26, v26
	v_mul_f32_e32 v5, v5, v27
	v_mul_f32_e32 v19, v19, v20
	v_mul_f32_e32 v11, v11, v21
	v_mul_f32_e32 v15, v15, v22
	v_mul_f32_e32 v13, v13, v23
	v_mul_f32_e32 v17, v17, v24
	v_mul_f32_e32 v3, v3, v25
	v_mul_f32_e32 v7, v7, v26
	v_mul_f32_e32 v5, v4, v5
	s_mov_b64 s[0:1], -1
	v_mul_f32_e32 v18, v18, v19
	v_mul_f32_e32 v10, v10, v11
	v_mul_f32_e32 v11, v14, v15
	v_mul_f32_e32 v12, v12, v13
	v_mul_f32_e32 v13, v16, v17
	v_mul_f32_e32 v14, v2, v3
	v_mul_f32_e32 v6, v6, v7
	v_cvt_pk_bf16_f32 v2, v18, v10
	v_cvt_pk_bf16_f32 v3, v11, v12
	v_cvt_pk_bf16_f32 v4, v13, v14
	v_cvt_pk_bf16_f32 v5, v6, v5
	global_store_dwordx4 v[8:9], v[2:5], off
	s_cbranch_vccnz .LBB0_1325
	s_andn2_b64 vcc, exec, s[8:9]
	s_cbranch_vccnz .LBB0_1324
	s_barrier
	s_branch .LBB0_1324

	.amdhsa_kernel _Z10fwd_kernel4Args
		.amdhsa_group_segment_fixed_size 0
		.amdhsa_private_segment_fixed_size 0
		.amdhsa_kernarg_size 432
		.amdhsa_user_sgpr_count 2
		.amdhsa_user_sgpr_dispatch_ptr 0
		.amdhsa_user_sgpr_queue_ptr 0
		.amdhsa_user_sgpr_kernarg_segment_ptr 1
		.amdhsa_user_sgpr_dispatch_id 0
		.amdhsa_user_sgpr_kernarg_preload_length 0
		.amdhsa_user_sgpr_kernarg_preload_offset 0
		.amdhsa_user_sgpr_private_segment_size 0
		.amdhsa_uses_dynamic_stack 0
		.amdhsa_enable_private_segment 0
		.amdhsa_system_sgpr_workgroup_id_x 1
		.amdhsa_system_sgpr_workgroup_id_y 0
		.amdhsa_system_sgpr_workgroup_id_z 0
		.amdhsa_system_sgpr_workgroup_info 0
		.amdhsa_system_vgpr_workitem_id 2
		.amdhsa_next_free_vgpr 256
		.amdhsa_next_free_sgpr 98
		.amdhsa_accum_offset 256
		.amdhsa_reserve_vcc 1
		.amdhsa_float_round_mode_32 0
		.amdhsa_float_round_mode_16_64 0
		.amdhsa_float_denorm_mode_32 3
		.amdhsa_float_denorm_mode_16_64 3
		.amdhsa_dx10_clamp 1
		.amdhsa_ieee_mode 1
		.amdhsa_fp16_overflow 0
		.amdhsa_tg_split 0
		.amdhsa_exception_fp_ieee_invalid_op 0
		.amdhsa_exception_fp_denorm_src 0
		.amdhsa_exception_fp_ieee_div_zero 0
		.amdhsa_exception_fp_ieee_overflow 0
		.amdhsa_exception_fp_ieee_underflow 0
		.amdhsa_exception_fp_ieee_inexact 0
		.amdhsa_exception_int_div_zero 0
	.end_amdhsa_kernel

.Lfunc_end0:
	.size	_Z10fwd_kernel4Args, .Lfunc_end0-_Z10fwd_kernel4Args
	.set _Z10fwd_kernel4Args.num_vgpr, 256
	.set _Z10fwd_kernel4Args.num_agpr, 0
	.set _Z10fwd_kernel4Args.numbered_sgpr, 98
	.set _Z10fwd_kernel4Args.num_named_barrier, 0
	.set _Z10fwd_kernel4Args.private_seg_size, 0
	.set _Z10fwd_kernel4Args.uses_vcc, 1
	.set _Z10fwd_kernel4Args.uses_flat_scratch, 0
	.set _Z10fwd_kernel4Args.has_dyn_sized_stack, 0
	.set _Z10fwd_kernel4Args.has_recursion, 0
	.set _Z10fwd_kernel4Args.has_indirect_call, 0

amdhsa.kernels:
  - .agpr_count:     0
    .args:
      - .offset:         0
        .size:           176
        .value_kind:     by_value
      - .offset:         176
        .size:           4
        .value_kind:     hidden_block_count_x
      - .offset:         180
        .size:           4
        .value_kind:     hidden_block_count_y
      - .offset:         184
        .size:           4
        .value_kind:     hidden_block_count_z
      - .offset:         188
        .size:           2
        .value_kind:     hidden_group_size_x
      - .offset:         190
        .size:           2
        .value_kind:     hidden_group_size_y
      - .offset:         192
        .size:           2
        .value_kind:     hidden_group_size_z
      - .offset:         194
        .size:           2
        .value_kind:     hidden_remainder_x
      - .offset:         196
        .size:           2
        .value_kind:     hidden_remainder_y
      - .offset:         198
        .size:           2
        .value_kind:     hidden_remainder_z
      - .offset:         216
        .size:           8
        .value_kind:     hidden_global_offset_x
      - .offset:         224
        .size:           8
        .value_kind:     hidden_global_offset_y
      - .offset:         232
        .size:           8
        .value_kind:     hidden_global_offset_z
      - .offset:         240
        .size:           2
        .value_kind:     hidden_grid_dims
      - .offset:         264
        .size:           8
        .value_kind:     hidden_multigrid_sync_arg
      - .offset:         296
        .size:           4
        .value_kind:     hidden_dynamic_lds_size
    .group_segment_fixed_size: 0
    .kernarg_segment_align: 8
    .kernarg_segment_size: 432
    .language:       OpenCL C
    .language_version:
      - 2
      - 0
    .max_flat_workgroup_size: 512
    .name:           _Z10fwd_kernel4Args
    .private_segment_fixed_size: 0
    .sgpr_count:     104
    .sgpr_spill_count: 24
    .symbol:         _Z10fwd_kernel4Args.kd
    .uniform_work_group_size: 1
    .uses_dynamic_stack: false
    .vgpr_count:     256
    .vgpr_spill_count: 0
    .wavefront_size: 64
